# attention: running-shift QK variant moved out of line; the common QK block falls straight into the shift test (no test + taken branch per 32-key half)
# speedup vs baseline: 1.0050x; 1.0050x over previous
.LBB0_882:
	v_mad_u32_u24 v212, v203, s82, v201
	ds_read_b128 v[64:67], v212
	ds_read_b128 v[204:207], v212 offset:32
	s_mov_b64 s[28:29], 0
	ds_read_b128 v[208:211], v212 offset:64
	ds_read_b128 v[246:249], v212 offset:96
	s_waitcnt lgkmcnt(2)
	v_mfma_f32_32x32x16_bf16 v[80:95], v[64:67], v[96:99], 0
	v_mfma_f32_32x32x16_bf16 v[64:79], v[64:67], v[136:139], 0
	v_mfma_f32_32x32x16_bf16 v[80:95], v[204:207], v[100:103], v[80:95]
	v_mfma_f32_32x32x16_bf16 v[64:79], v[204:207], v[120:123], v[64:79]
	ds_read_b128 v[204:207], v212 offset:128
	ds_read_b128 v[250:253], v212 offset:160
	s_waitcnt lgkmcnt(2)
	v_mfma_f32_32x32x16_bf16 v[80:95], v[208:211], v[104:107], v[80:95]
	v_mfma_f32_32x32x16_bf16 v[64:79], v[208:211], v[124:127], v[64:79]
	v_mfma_f32_32x32x16_bf16 v[80:95], v[246:249], v[108:111], v[80:95]
	v_mfma_f32_32x32x16_bf16 v[64:79], v[246:249], v[128:131], v[64:79]
	s_waitcnt lgkmcnt(0)
	v_mfma_f32_32x32x16_bf16 v[80:95], v[204:207], v[112:115], v[80:95]
	v_mfma_f32_32x32x16_bf16 v[64:79], v[204:207], v[132:135], v[64:79]
	v_mfma_f32_32x32x16_bf16 v[80:95], v[250:253], v[116:119], v[80:95]
	v_mfma_f32_32x32x16_bf16 v[64:79], v[250:253], v[140:143], v[64:79]
.LBB0_885:
	s_nop 8
	s_cmp_lg_u64 s[64:65], 0
	s_cbranch_scc1 .Lhwat0_full
	v_max_f32_e32 v203, v80, v81
	v_max_f32_e32 v205, v64, v65
	v_max3_f32 v203, v203, v82, v83
	v_max3_f32 v205, v205, v66, v67
	v_max3_f32 v203, v203, v84, v85
	v_max3_f32 v205, v205, v68, v69
	v_max3_f32 v203, v203, v86, v87
	v_max3_f32 v205, v205, v70, v71
	v_max3_f32 v203, v203, v88, v89
	v_max3_f32 v205, v205, v72, v73
	v_max3_f32 v203, v203, v90, v91
	v_max3_f32 v205, v205, v74, v75
	v_max3_f32 v203, v203, v92, v93
	v_max3_f32 v205, v205, v76, v77
	v_max3_f32 v203, v203, v94, v95
	v_max3_f32 v205, v205, v78, v79
	v_max_f32_e32 v204, v203, v205
	v_cmp_lt_f32_e32 vcc, s83, v204
	s_cbranch_vccz .LBB0_887

.LBB0_883:
	s_andn2_b64 vcc, exec, s[28:29]
	s_cbranch_vccnz .LBB0_885
	v_mad_u32_u24 v203, v203, s82, v201
	ds_read_b128 v[204:207], v203
	ds_read_b128 v[208:211], v203 offset:32
	s_nop 5
	v_xor_b32_e32 v80, 0x80000000, v199
	v_xor_b32_e32 v64, 0x80000000, v200
	v_mov_b32_e32 v81, v80
	v_mov_b32_e32 v82, v80
	v_mov_b32_e32 v83, v80
	v_mov_b32_e32 v84, v80
	v_mov_b32_e32 v85, v80
	v_mov_b32_e32 v86, v80
	v_mov_b32_e32 v87, v80
	v_mov_b32_e32 v88, v80
	v_mov_b32_e32 v89, v80
	v_mov_b32_e32 v90, v80
	v_mov_b32_e32 v91, v80
	v_mov_b32_e32 v92, v80
	v_mov_b32_e32 v93, v80
	v_mov_b32_e32 v94, v80
	v_mov_b32_e32 v95, v80
	v_mov_b32_e32 v65, v64
	v_mov_b32_e32 v66, v64
	v_mov_b32_e32 v67, v64
	v_mov_b32_e32 v68, v64
	v_mov_b32_e32 v69, v64
	v_mov_b32_e32 v70, v64
	v_mov_b32_e32 v71, v64
	v_mov_b32_e32 v72, v64
	v_mov_b32_e32 v73, v64
	v_mov_b32_e32 v74, v64
	v_mov_b32_e32 v75, v64
	v_mov_b32_e32 v76, v64
	v_mov_b32_e32 v77, v64
	v_mov_b32_e32 v78, v64
	v_mov_b32_e32 v79, v64
	s_waitcnt lgkmcnt(0)
	v_mfma_f32_32x32x16_bf16 v[80:95], v[204:207], v[96:99], v[80:95]
	v_mfma_f32_32x32x16_bf16 v[64:79], v[204:207], v[136:139], v[64:79]
	v_mfma_f32_32x32x16_bf16 v[80:95], v[208:211], v[100:103], v[80:95]
	v_mfma_f32_32x32x16_bf16 v[64:79], v[208:211], v[120:123], v[64:79]
	ds_read_b128 v[204:207], v203 offset:64
	ds_read_b128 v[208:211], v203 offset:96
	s_waitcnt lgkmcnt(0)
	v_mfma_f32_32x32x16_bf16 v[80:95], v[204:207], v[104:107], v[80:95]
	v_mfma_f32_32x32x16_bf16 v[64:79], v[204:207], v[124:127], v[64:79]
	v_mfma_f32_32x32x16_bf16 v[80:95], v[208:211], v[108:111], v[80:95]
	v_mfma_f32_32x32x16_bf16 v[64:79], v[208:211], v[128:131], v[64:79]
	ds_read_b128 v[204:207], v203 offset:128
	ds_read_b128 v[208:211], v203 offset:160
	s_waitcnt lgkmcnt(0)
	v_mfma_f32_32x32x16_bf16 v[80:95], v[204:207], v[112:115], v[80:95]
	v_mfma_f32_32x32x16_bf16 v[64:79], v[204:207], v[132:135], v[64:79]
	v_mfma_f32_32x32x16_bf16 v[80:95], v[208:211], v[116:119], v[80:95]
	v_mfma_f32_32x32x16_bf16 v[64:79], v[208:211], v[140:143], v[64:79]
	s_branch .LBB0_885

.LBB0_2116:
	v_mad_u32_u24 v212, v203, s81, v201
	ds_read_b128 v[64:67], v212
	ds_read_b128 v[204:207], v212 offset:32
	s_mov_b64 s[34:35], 0
	ds_read_b128 v[208:211], v212 offset:64
	ds_read_b128 v[246:249], v212 offset:96
	s_waitcnt lgkmcnt(2)
	v_mfma_f32_32x32x16_bf16 v[80:95], v[64:67], v[96:99], 0
	v_mfma_f32_32x32x16_bf16 v[64:79], v[64:67], v[136:139], 0
	v_mfma_f32_32x32x16_bf16 v[80:95], v[204:207], v[100:103], v[80:95]
	v_mfma_f32_32x32x16_bf16 v[64:79], v[204:207], v[120:123], v[64:79]
	ds_read_b128 v[204:207], v212 offset:128
	ds_read_b128 v[250:253], v212 offset:160
	s_waitcnt lgkmcnt(2)
	v_mfma_f32_32x32x16_bf16 v[80:95], v[208:211], v[104:107], v[80:95]
	v_mfma_f32_32x32x16_bf16 v[64:79], v[208:211], v[124:127], v[64:79]
	v_mfma_f32_32x32x16_bf16 v[80:95], v[246:249], v[108:111], v[80:95]
	v_mfma_f32_32x32x16_bf16 v[64:79], v[246:249], v[128:131], v[64:79]
	s_waitcnt lgkmcnt(0)
	v_mfma_f32_32x32x16_bf16 v[80:95], v[204:207], v[112:115], v[80:95]
	v_mfma_f32_32x32x16_bf16 v[64:79], v[204:207], v[132:135], v[64:79]
	v_mfma_f32_32x32x16_bf16 v[80:95], v[250:253], v[116:119], v[80:95]
	v_mfma_f32_32x32x16_bf16 v[64:79], v[250:253], v[140:143], v[64:79]
.LBB0_2119:
	s_nop 8
	s_cmp_lg_u64 s[64:65], 0
	s_cbranch_scc1 .Lhwat1_full
	v_max_f32_e32 v203, v80, v81
	v_max_f32_e32 v205, v64, v65
	v_max3_f32 v203, v203, v82, v83
	v_max3_f32 v205, v205, v66, v67
	v_max3_f32 v203, v203, v84, v85
	v_max3_f32 v205, v205, v68, v69
	v_max3_f32 v203, v203, v86, v87
	v_max3_f32 v205, v205, v70, v71
	v_max3_f32 v203, v203, v88, v89
	v_max3_f32 v205, v205, v72, v73
	v_max3_f32 v203, v203, v90, v91
	v_max3_f32 v205, v205, v74, v75
	v_max3_f32 v203, v203, v92, v93
	v_max3_f32 v205, v205, v76, v77
	v_max3_f32 v203, v203, v94, v95
	v_max3_f32 v205, v205, v78, v79
	v_max_f32_e32 v204, v203, v205
	v_cmp_lt_f32_e32 vcc, s82, v204
	s_cbranch_vccz .LBB0_2121

.LBB0_2117:
	s_andn2_b64 vcc, exec, s[34:35]
	s_cbranch_vccnz .LBB0_2119
	v_mad_u32_u24 v203, v203, s81, v201
	ds_read_b128 v[204:207], v203
	ds_read_b128 v[208:211], v203 offset:32
	s_nop 5
	v_xor_b32_e32 v80, 0x80000000, v199
	v_xor_b32_e32 v64, 0x80000000, v200
	v_mov_b32_e32 v81, v80
	v_mov_b32_e32 v82, v80
	v_mov_b32_e32 v83, v80
	v_mov_b32_e32 v84, v80
	v_mov_b32_e32 v85, v80
	v_mov_b32_e32 v86, v80
	v_mov_b32_e32 v87, v80
	v_mov_b32_e32 v88, v80
	v_mov_b32_e32 v89, v80
	v_mov_b32_e32 v90, v80
	v_mov_b32_e32 v91, v80
	v_mov_b32_e32 v92, v80
	v_mov_b32_e32 v93, v80
	v_mov_b32_e32 v94, v80
	v_mov_b32_e32 v95, v80
	v_mov_b32_e32 v65, v64
	v_mov_b32_e32 v66, v64
	v_mov_b32_e32 v67, v64
	v_mov_b32_e32 v68, v64
	v_mov_b32_e32 v69, v64
	v_mov_b32_e32 v70, v64
	v_mov_b32_e32 v71, v64
	v_mov_b32_e32 v72, v64
	v_mov_b32_e32 v73, v64
	v_mov_b32_e32 v74, v64
	v_mov_b32_e32 v75, v64
	v_mov_b32_e32 v76, v64
	v_mov_b32_e32 v77, v64
	v_mov_b32_e32 v78, v64
	v_mov_b32_e32 v79, v64
	s_waitcnt lgkmcnt(0)
	v_mfma_f32_32x32x16_bf16 v[80:95], v[204:207], v[96:99], v[80:95]
	v_mfma_f32_32x32x16_bf16 v[64:79], v[204:207], v[136:139], v[64:79]
	v_mfma_f32_32x32x16_bf16 v[80:95], v[208:211], v[100:103], v[80:95]
	v_mfma_f32_32x32x16_bf16 v[64:79], v[208:211], v[120:123], v[64:79]
	ds_read_b128 v[204:207], v203 offset:64
	ds_read_b128 v[208:211], v203 offset:96
	s_waitcnt lgkmcnt(0)
	v_mfma_f32_32x32x16_bf16 v[80:95], v[204:207], v[104:107], v[80:95]
	v_mfma_f32_32x32x16_bf16 v[64:79], v[204:207], v[124:127], v[64:79]
	v_mfma_f32_32x32x16_bf16 v[80:95], v[208:211], v[108:111], v[80:95]
	v_mfma_f32_32x32x16_bf16 v[64:79], v[208:211], v[128:131], v[64:79]
	ds_read_b128 v[204:207], v203 offset:128
	ds_read_b128 v[208:211], v203 offset:160
	s_waitcnt lgkmcnt(0)
	v_mfma_f32_32x32x16_bf16 v[80:95], v[204:207], v[112:115], v[80:95]
	v_mfma_f32_32x32x16_bf16 v[64:79], v[204:207], v[132:135], v[64:79]
	v_mfma_f32_32x32x16_bf16 v[80:95], v[208:211], v[116:119], v[80:95]
	v_mfma_f32_32x32x16_bf16 v[64:79], v[208:211], v[140:143], v[64:79]
	s_branch .LBB0_2119
